# lever 2: layer-0 gres16 + gres44 epilogue residual loads de-serialised (both)
# speedup vs baseline: 1.0072x; 1.0072x over previous
.LBB0_950:
	v_lshl_add_u32 v66, s92, 7, v99
	v_ashrrev_i32_e32 v67, 31, v66
	v_readlane_b32 s12, v254, 3
	v_lshlrev_b64 v[68:69], 12, v[66:67]
	v_readlane_b32 s26, v254, 17
	v_readlane_b32 s27, v254, 18
	s_waitcnt vmcnt(0)
	s_barrier
	v_lshl_add_u64 v[70:71], s[26:27], 0, v[68:69]
	v_lshl_or_b32 v68, s91, 7, v98
	v_ashrrev_i32_e32 v69, 31, v68
	v_lshlrev_b64 v[68:69], 2, v[68:69]
	v_lshl_add_u64 v[74:75], v[70:71], 0, v[68:69]
	v_or_b32_e32 v170, 16, v66
	v_ashrrev_i32_e32 v171, 31, v170
	v_lshlrev_b64 v[170:171], 12, v[170:171]
	v_lshl_add_u64 v[170:171], s[26:27], 0, v[170:171]
	v_lshl_add_u64 v[170:171], v[170:171], 0, v[68:69]
	v_or_b32_e32 v172, 32, v66
	v_ashrrev_i32_e32 v173, 31, v172
	v_lshlrev_b64 v[172:173], 12, v[172:173]
	v_lshl_add_u64 v[172:173], s[26:27], 0, v[172:173]
	v_lshl_add_u64 v[172:173], v[172:173], 0, v[68:69]
	v_or_b32_e32 v176, 48, v66
	v_ashrrev_i32_e32 v177, 31, v176
	v_lshlrev_b64 v[176:177], 12, v[176:177]
	v_lshl_add_u64 v[176:177], s[26:27], 0, v[176:177]
	v_lshl_add_u64 v[176:177], v[176:177], 0, v[68:69]
	global_load_dwordx4 v[82:85], v[74:75], off
	global_load_dwordx4 v[86:89], v[74:75], off offset:64
	global_load_dwordx4 v[90:93], v[74:75], off offset:128
	global_load_dwordx4 v[94:97], v[74:75], off offset:192
	global_load_dwordx4 v[122:125], v[170:171], off
	global_load_dwordx4 v[126:129], v[170:171], off offset:64
	global_load_dwordx4 v[130:133], v[170:171], off offset:128
	global_load_dwordx4 v[134:137], v[170:171], off offset:192
	global_load_dwordx4 v[138:141], v[172:173], off
	global_load_dwordx4 v[142:145], v[172:173], off offset:64
	global_load_dwordx4 v[146:149], v[172:173], off offset:128
	global_load_dwordx4 v[150:153], v[172:173], off offset:192
	global_load_dwordx4 v[154:157], v[176:177], off
	global_load_dwordx4 v[158:161], v[176:177], off offset:64
	global_load_dwordx4 v[162:165], v[176:177], off offset:128
	global_load_dwordx4 v[166:169], v[176:177], off offset:192
	s_add_i32 s3, s3, s85
	s_add_i32 s90, s90, s28
	s_cmpk_gt_i32 s3, 0x87
	v_readlane_b32 s13, v254, 4
	v_readlane_b32 s14, v254, 5
	v_readlane_b32 s15, v254, 6
	v_readlane_b32 s16, v254, 7
	v_readlane_b32 s17, v254, 8
	v_readlane_b32 s18, v254, 9
	v_readlane_b32 s19, v254, 10
	v_readlane_b32 s20, v254, 11
	v_readlane_b32 s21, v254, 12
	v_readlane_b32 s22, v254, 13
	v_readlane_b32 s23, v254, 14
	v_readlane_b32 s24, v254, 15
	v_readlane_b32 s25, v254, 16
	s_waitcnt vmcnt(15)
	v_pk_add_f32 v[60:61], v[60:61], v[82:83]
	v_pk_add_f32 v[62:63], v[62:63], v[84:85]
	s_waitcnt vmcnt(14)
	v_pk_add_f32 v[56:57], v[56:57], v[86:87]
	v_pk_add_f32 v[58:59], v[58:59], v[88:89]
	s_waitcnt vmcnt(13)
	v_pk_add_f32 v[52:53], v[52:53], v[90:91]
	v_pk_add_f32 v[54:55], v[54:55], v[92:93]
	s_waitcnt vmcnt(12)
	v_pk_add_f32 v[48:49], v[48:49], v[94:95]
	v_pk_add_f32 v[50:51], v[50:51], v[96:97]
	s_waitcnt vmcnt(11)
	v_pk_add_f32 v[44:45], v[44:45], v[122:123]
	v_pk_add_f32 v[46:47], v[46:47], v[124:125]
	s_waitcnt vmcnt(10)
	v_pk_add_f32 v[40:41], v[40:41], v[126:127]
	v_pk_add_f32 v[42:43], v[42:43], v[128:129]
	s_waitcnt vmcnt(9)
	v_pk_add_f32 v[36:37], v[36:37], v[130:131]
	v_pk_add_f32 v[38:39], v[38:39], v[132:133]
	s_waitcnt vmcnt(8)
	v_pk_add_f32 v[32:33], v[32:33], v[134:135]
	v_pk_add_f32 v[34:35], v[34:35], v[136:137]
	s_waitcnt vmcnt(7)
	v_pk_add_f32 v[28:29], v[28:29], v[138:139]
	v_pk_add_f32 v[30:31], v[30:31], v[140:141]
	s_waitcnt vmcnt(6)
	v_pk_add_f32 v[24:25], v[24:25], v[142:143]
	v_pk_add_f32 v[26:27], v[26:27], v[144:145]
	s_waitcnt vmcnt(5)
	v_pk_add_f32 v[20:21], v[20:21], v[146:147]
	v_pk_add_f32 v[22:23], v[22:23], v[148:149]
	s_waitcnt vmcnt(4)
	v_pk_add_f32 v[16:17], v[16:17], v[150:151]
	v_pk_add_f32 v[18:19], v[18:19], v[152:153]
	s_waitcnt vmcnt(3)
	v_pk_add_f32 v[12:13], v[12:13], v[154:155]
	v_pk_add_f32 v[14:15], v[14:15], v[156:157]
	s_waitcnt vmcnt(2)
	v_pk_add_f32 v[8:9], v[8:9], v[158:159]
	v_pk_add_f32 v[10:11], v[10:11], v[160:161]
	s_waitcnt vmcnt(1)
	v_pk_add_f32 v[4:5], v[4:5], v[162:163]
	v_pk_add_f32 v[6:7], v[6:7], v[164:165]
	s_waitcnt vmcnt(0)
	v_pk_add_f32 v[0:1], v[0:1], v[166:167]
	v_pk_add_f32 v[2:3], v[2:3], v[168:169]
	global_store_dwordx4 v[74:75], v[60:63], off
	global_store_dwordx4 v[74:75], v[56:59], off offset:64
	global_store_dwordx4 v[74:75], v[52:55], off offset:128
	global_store_dwordx4 v[74:75], v[48:51], off offset:192
	global_store_dwordx4 v[170:171], v[44:47], off
	global_store_dwordx4 v[170:171], v[40:43], off offset:64
	global_store_dwordx4 v[170:171], v[36:39], off offset:128
	global_store_dwordx4 v[170:171], v[32:35], off offset:192
	global_store_dwordx4 v[172:173], v[28:31], off
	global_store_dwordx4 v[172:173], v[24:27], off offset:64
	global_store_dwordx4 v[172:173], v[20:23], off offset:128
	global_store_dwordx4 v[172:173], v[16:19], off offset:192
	global_store_dwordx4 v[176:177], v[12:15], off
	global_store_dwordx4 v[176:177], v[8:11], off offset:64
	global_store_dwordx4 v[176:177], v[4:7], off offset:128
	global_store_dwordx4 v[176:177], v[0:3], off offset:192
	s_cbranch_scc1 .LBB0_955
